# adds: QKV up-projection GEMM tiles reordered so each CU processes consecutive column tiles of the same row tile (L2 reuse of A rows and epilogue inputs)
# speedup vs baseline: 1.0186x; 1.0057x over previous
;   DI bool next(int i, Unit& u) const {
;     const long L = (long)i * G + c; if (L >= nwg) return false;
;     int wgid = (int)L; { const int q = nwg / NXCD, r = nwg % NXCD, xcd = wgid % NXCD, off = wgid / NXCD; wgid = (xcd < r ? xcd * (q + 1) : r * (q + 1) + (xcd - r) * q) + off; }
;     const int nig = WGM * nN, gid = wgid / nig, fm = gid * WGM, gsz = (nM - fm) < WGM ? (nM - fm) : WGM;
;     u.pm = pm_off + fm + ((wgid % nig) % gsz); u.pn = (wgid % nig) / gsz; return true;
; __global__ void __launch_bounds__(512, 2) mega(Params p) {
;     ...
;             const int Gq = G - half, cq_ = bid - half, Kq = pass ? 128 : 256;
;             run_gemm(lds, tid, (const bf16_t*)(ws + OFF_LAT) + pass * 256, (const bf16_t*)(wl + WO_QKV) + (size_t)pass * 1024 * 256, T, 1024, Kq, e, Gq, (cq_ + pass * (Gq >> 1)) % Gq, 0, 384, Kq); }
.LBB0_577:
	v_readlane_b32 s4, v253, 0
	v_readlane_b32 s5, v253, 1
	v_readlane_b32 s6, v253, 2
	v_readlane_b32 s7, v253, 3
	v_readlane_b32 s8, v253, 4
	v_readlane_b32 s9, v253, 5
	v_readlane_b32 s10, v253, 6
	v_readlane_b32 s11, v253, 7
	s_mov_b64 s[4:5], s[8:9]
	s_mov_b64 s[6:7], s[10:11]
	v_mov_b32_e32 v21, v186
	s_mov_b64 s[0:1], s[6:7]
	v_readlane_b32 s3, v254, 1
	s_mul_i32 s3, s2, s3
	v_readlane_b32 s4, v254, 6
	s_add_i32 s3, s4, s3
	s_ashr_i32 s4, s3, 31
	s_abs_i32 s3, s3
	v_readlane_b32 s5, v254, 43
	s_mul_hi_u32 s5, s3, s5
	v_readlane_b32 s6, v254, 42
	s_mul_i32 s5, s5, s6
	s_sub_i32 s3, s3, s5
	s_sub_i32 s5, s3, s6
	s_cmp_ge_u32 s3, s6
	s_cselect_b32 s3, s5, s3
	s_sub_i32 s5, s3, s6
	s_cmp_ge_u32 s3, s6
	s_cselect_b32 s3, s5, s3
	s_xor_b32 s3, s3, s4
	s_sub_i32 s40, s3, s4
	s_cmpk_lt_i32 s40, 0x240
	s_cselect_b64 s[4:5], -1, 0
	s_cmpk_gt_i32 s40, 0x23f
	v_readfirstlane_b32 s81, v21
	s_cbranch_scc1 .LBB0_579
	s_and_b32 s98, s40, 0x7f
	s_lshr_b32 s99, s40, 7
	s_mul_i32 s100, s98, 5
	s_lshl_b32 s101, s98, 2
	s_add_i32 s101, s101, 64
	s_cmp_lt_u32 s98, 64
	s_cselect_b32 s98, s100, s101
	s_add_i32 s98, s98, s99
	s_lshr_b32 s99, s98, 2
	s_and_b32 s98, s98, 3
	s_lshr_b32 s100, s99, 3
	s_lshl_b32 s100, s100, 5
	s_lshl_b32 s98, s98, 3
	s_add_i32 s100, s100, s98
	s_and_b32 s99, s99, 7
	s_add_i32 s100, s100, s99
	s_mul_i32 s98, s100, 0x38f
	s_lshr_b32 s98, s98, 16
	s_mul_i32 s99, s98, 0x48
	s_sub_i32 s99, s100, s99
	s_lshl_b32 s99, s99, 3
	s_add_i32 s98, s99, s98
	s_ashr_i32 s3, s98, 31
	s_lshr_b32 s3, s3, 29
	s_add_i32 s3, s98, s3
	s_ashr_i32 s6, s3, 3
	s_and_b32 s3, s3, -8
	s_sub_i32 s3, s98, s3
	s_cmp_lt_i32 s3, 0
	s_movk_i32 s7, 0x49
	s_cselect_b32 s7, s7, 0x48
	s_mul_i32 s3, s7, s3
	s_add_i32 s3, s3, s6
	s_ashr_i32 s6, s3, 31
	s_lshr_b32 s6, s6, 27
	s_add_i32 s6, s3, s6
	s_ashr_i32 s7, s6, 5
	s_and_b32 s6, s6, 0xffe0
	s_sub_i32 s3, s3, s6
	s_bfe_i32 s6, s3, 0x80000
	s_bfe_u32 s6, s6, 0x3000c
	s_add_i32 s6, s3, s6
	s_bfe_i32 s8, s6, 0x80000
	s_and_b32 s6, s6, 0xf8
	s_sub_i32 s3, s3, s6
	s_lshl_b32 s7, s7, 3
	s_sext_i32_i16 s8, s8
	s_sext_i32_i8 s3, s3
	s_add_i32 s80, s7, s3
	s_ashr_i32 s8, s8, 3

;   DI bool next(int i, Unit& u) const {
;     const long L = (long)i * G + c; if (L >= nwg) return false;
;     int wgid = (int)L; { const int q = nwg / NXCD, r = nwg % NXCD, xcd = wgid % NXCD, off = wgid / NXCD; wgid = (xcd < r ? xcd * (q + 1) : r * (q + 1) + (xcd - r) * q) + off; }
;     const int nig = WGM * nN, gid = wgid / nig, fm = gid * WGM, gsz = (nM - fm) < WGM ? (nM - fm) : WGM;
;     u.pm = pm_off + fm + ((wgid % nig) % gsz); u.pn = (wgid % nig) / gsz; return true;
; template <class Epi, class Sched>
; DI void gemm_phase(LAS unsigned char* lds, const int tid, const Gemm g, const Sched& S, const Epi& E) {
;     ...
;     const bool has_next = S.next(ui + 1, nxt);
;     const char* nA = has_next ? (const char*)g.A + (size_t)nxt.pm * tstepA : cA; const char* nB = has_next ? (const char*)g.Bt + (size_t)nxt.pn * tstepB : cB;
.LBB0_584:
	s_add_i32 s91, s91, 1
	v_readlane_b32 s0, v254, 2
	v_readlane_b32 s6, v254, 39
	s_mul_i32 s0, s91, s0
	s_mul_hi_u32 s1, s91, s6
	s_add_i32 s1, s1, s0
	s_mul_i32 s0, s91, s6
	s_add_u32 s14, s0, s40
	s_addc_u32 s15, s1, s41
	v_cmp_gt_i64_e64 s[6:7], s[14:15], v[194:195]
	v_cmp_lt_i64_e64 s[0:1], s[14:15], v[196:197]
	s_and_b64 vcc, exec, s[6:7]
	s_cbranch_vccnz .LBB0_586
	s_and_b32 s98, s14, 0x7f
	s_lshr_b32 s99, s14, 7
	s_mul_i32 s100, s98, 5
	s_lshl_b32 s101, s98, 2
	s_add_i32 s101, s101, 64
	s_cmp_lt_u32 s98, 64
	s_cselect_b32 s98, s100, s101
	s_add_i32 s98, s98, s99
	s_lshr_b32 s99, s98, 2
	s_and_b32 s98, s98, 3
	s_lshr_b32 s100, s99, 3
	s_lshl_b32 s100, s100, 5
	s_lshl_b32 s98, s98, 3
	s_add_i32 s100, s100, s98
	s_and_b32 s99, s99, 7
	s_add_i32 s100, s100, s99
	s_mul_i32 s98, s100, 0x38f
	s_lshr_b32 s98, s98, 16
	s_mul_i32 s99, s98, 0x48
	s_sub_i32 s99, s100, s99
	s_lshl_b32 s99, s99, 3
	s_add_i32 s14, s99, s98
	s_ashr_i32 s9, s14, 31
	s_lshr_b32 s9, s9, 29
	s_add_i32 s9, s14, s9
	s_ashr_i32 s15, s9, 3
	s_and_b32 s9, s9, -8
	s_sub_i32 s9, s14, s9
	s_cmp_lt_i32 s9, 0
	s_movk_i32 s14, 0x49
	s_cselect_b32 s14, s14, 0x48
	s_mul_i32 s9, s14, s9
	s_add_i32 s9, s9, s15
	s_ashr_i32 s14, s9, 31
	s_lshr_b32 s14, s14, 27
	s_add_i32 s14, s9, s14
	s_ashr_i32 s15, s14, 5
	s_lshl_b32 s15, s15, 3
	s_sub_i32 s22, 0x90, s15
	s_min_i32 s23, s22, 8
	s_abs_i32 s22, s23
	v_cvt_f32_u32_e32 v0, s22
	s_sub_i32 s25, 0, s22
	s_andn2_b32 s14, s14, 31
	s_sub_i32 s9, s9, s14
	v_rcp_iflag_f32_e32 v0, v0
	s_abs_i32 s14, s9
	s_xor_b32 s24, s9, s23
	s_ashr_i32 s24, s24, 31
	v_mul_f32_e32 v0, 0x4f7ffffe, v0
	v_cvt_u32_f32_e32 v0, v0
	s_nop 0
	v_readfirstlane_b32 s26, v0
	s_mul_i32 s25, s25, s26
	s_mul_hi_u32 s25, s26, s25
	s_add_i32 s26, s26, s25
	s_mul_hi_u32 s25, s14, s26
	s_mul_i32 s26, s25, s22
	s_sub_i32 s14, s14, s26
	s_add_i32 s27, s25, 1
	s_sub_i32 s26, s14, s22
	s_cmp_ge_u32 s14, s22
	s_cselect_b32 s25, s27, s25
	s_cselect_b32 s14, s26, s14
	s_add_i32 s26, s25, 1
	s_cmp_ge_u32 s14, s22
	s_cselect_b32 s14, s26, s25
	s_xor_b32 s14, s14, s24
	s_sub_i32 s22, s14, s24
	s_mul_i32 s14, s22, s23
	s_sub_i32 s9, s9, s14
	s_add_i32 s76, s9, s15
